# PRE phase: static s_setprio 1 for team 1 (waves 4-7) during the item loop
# baseline (speedup 1.0000x reference)
.LBB0_78:
	s_or_b64 exec, exec, s[38:39]
	v_readlane_b32 s0, v252, 22
	v_readlane_b32 s1, v252, 23
	s_andn2_b64 vcc, exec, s[0:1]
	s_cbranch_vccnz .LBB0_163
	s_ashr_i32 s0, s66, 2
	s_mul_i32 s1, s0, 0xfc00
	s_add_i32 s76, s1, 0
	s_lshl_b32 s1, s0, 8
	s_bfe_u32 s40, s66, 0x10001
	s_and_b32 s41, s66, 1
	s_add_i32 s26, s1, 0
	s_lshl_b32 s43, s40, 5
	s_lshl_b32 s91, s41, 5
	s_add_i32 s38, s76, 0x9000
	s_add_i32 s39, s76, 0xb400
	s_lshl_b32 s50, s0, 6
	s_add_i32 s87, s26, 0x24100
	s_add_u32 s48, s30, 0x6c00000
	s_addc_u32 s49, s31, 0
	s_ashr_i32 s1, s0, 31
	s_lshl_b64 s[24:25], s[0:1], 16
	s_add_u32 s3, s30, s24
	s_addc_u32 s24, s31, s25
	s_add_u32 s54, s3, 0x1b80000
	s_addc_u32 s55, s24, 0
	s_add_u32 s58, s3, 0x1ba0000
	s_addc_u32 s59, s24, 0
	s_lshl_b64 s[24:25], s[0:1], 19
	s_add_u32 s1, s30, s24
	s_addc_u32 s24, s31, s25
	s_lshl_b32 s3, s41, 8
	v_readlane_b32 s25, v252, 24
	s_or_b32 s77, s3, s25
	s_cmp_gt_u32 s66, 3
	s_cselect_b64 s[60:61], -1, 0
	s_lshl_b32 s25, s41, 7
	s_add_i32 s46, s26, s25
	s_add_i32 s47, s46, 0x24a00
	s_add_i32 s46, s46, 0x24c00
	s_lshl_b32 s28, s41, 6
	s_bitcmp1_b32 s66, 1
	s_cselect_b64 s[62:63], -1, 0
	s_lshl_b32 s0, s0, 9
	v_writelane_b32 v255, s96, 9
	s_add_i32 s25, s87, s25
	s_add_i32 s0, s0, 0
	v_writelane_b32 v255, s25, 10
	s_add_i32 s0, s0, 0x24300
	v_writelane_b32 v255, s0, 11
	s_add_i32 s0, s0, s3
	v_writelane_b32 v255, s0, 12
	s_cmp_eq_u32 s41, 0
	v_readlane_b32 s0, v253, 54
	s_cselect_b64 s[26:27], -1, 0
	s_add_u32 s0, s1, s0
	s_addc_u32 s1, s24, 0
	s_add_u32 s0, s0, 0x10400000
	s_addc_u32 s1, s1, 0
	s_cmp_lt_u32 s66, 4
	v_writelane_b32 v255, s0, 13
	s_cselect_b64 s[36:37], -1, 0
	s_nop 0
	v_writelane_b32 v255, s1, 14
	s_and_b64 s[0:1], s[36:37], exec
	v_readlane_b32 s0, v253, 61
	v_readlane_b32 s1, v253, 62
	s_cselect_b32 s29, s0, s1
	s_and_b32 s56, s66, 3
	s_cmp_eq_u32 s56, 0
	s_cselect_b64 s[72:73], -1, 0
	s_cmp_lg_u32 s56, 0
	s_cselect_b64 s[78:79], -1, 0
	s_cmp_eq_u32 s40, 0
	s_cselect_b64 s[24:25], -1, 0
	s_and_b64 s[0:1], s[24:25], exec
	s_cselect_b32 s1, s38, s39
	s_cmp_eq_u32 s40, s41
	s_cselect_b64 s[80:81], -1, 0
	s_lshl_b32 s0, s40, 6
	s_add_i32 s0, s76, s0
	s_and_b64 s[82:83], s[26:27], s[62:63]
	s_bitcmp1_b32 s66, 0
	s_cselect_b64 s[38:39], -1, 0
	s_and_b64 s[84:85], s[24:25], s[38:39]
	s_add_u32 s24, s30, 0xbc00000
	s_addc_u32 s25, s31, 0
	v_writelane_b32 v255, s24, 15
	s_brev_b32 s30, s56
	s_lshr_b32 s30, s30, 25
	v_writelane_b32 v255, s25, 16
	s_lshl_b32 s24, s40, 11
	s_lshl_b32 s25, s41, 10
	s_or_b32 s66, s24, s25
	v_readlane_b32 s24, v252, 25
	s_or_b32 s67, s77, 64
	s_or_b32 s94, s77, 0x80
	s_or_b32 s95, s77, 0xc0
	s_add_i32 s24, s50, s24
	s_or_b32 s25, s66, 0x200
	v_writelane_b32 v255, s30, 17
	s_xor_b64 s[96:97], s[26:27], -1
	v_readlane_b32 s26, v253, 51
	v_readlane_b32 s50, v252, 20
	s_and_b64 vcc, exec, s[60:61]
	s_cbranch_vccz .Lpre_prio_skip
	s_setprio 1
.Lpre_prio_skip:
	s_branch .LBB0_81
.LBB0_80:
	s_addk_i32 s26, 0x400
	s_andn2_b64 vcc, exec, s[30:31]
	s_mov_b32 s50, s27
	v_mov_b32_e32 v4, v20
	v_mov_b32_e32 v5, v21
	v_mov_b32_e32 v6, v22
	v_mov_b32_e32 v7, v23
	v_mov_b32_e32 v8, v24
	v_mov_b32_e32 v9, v25
	v_mov_b32_e32 v10, v26
	v_mov_b32_e32 v11, v27
	v_mov_b32_e32 v12, v28
	v_mov_b32_e32 v13, v29
	v_mov_b32_e32 v14, v30
	v_mov_b32_e32 v15, v31
	v_mov_b32_e32 v16, v32
	v_mov_b32_e32 v17, v33
	v_mov_b32_e32 v18, v34
	v_mov_b32_e32 v19, v35
	s_cbranch_vccz .LBB0_162

.LBB0_163:
	s_setprio 0
	v_readlane_b32 s0, v252, 6
	v_readlane_b32 s1, v252, 7
	s_andn2_b64 vcc, exec, s[0:1]
	s_mov_b64 s[26:27], 0
	v_cndmask_b32_e64 v1, 0, 1, s[0:1]
	v_cmp_ne_u32_e64 s[36:37], 1, v1
	s_cbranch_vccnz .LBB0_165
	v_mbcnt_lo_u32_b32 v1, -1, 0
	v_mbcnt_hi_u32_b32 v1, -1, v1
	s_nop 0
	v_cmp_eq_u32_e32 vcc, 0, v1
	s_and_b64 s[26:27], vcc, exec
